# ph3 GEMM epilogue: q-norm/k-norm gain vectors preloaded once per unit (64 per-step loads + vmcnt(0) waits removed), on top of ph6 epilogue pipeline + pool ring
# speedup vs baseline: 1.0339x; 1.0052x over previous
.LBB0_342:
	ds_read_b128 v[130:133], v182
	ds_read_b128 v[156:159], v182 offset:1024
	ds_read_b128 v[160:163], v182 offset:2048
	ds_read_b128 v[164:167], v182 offset:3072
	s_add_u32 s8, s6, 0xfff80080
	s_addc_u32 s9, s7, -1
	s_cmp_eq_u32 s39, 28
	s_cselect_b32 s11, s1, s9
	s_cselect_b32 s10, s3, s8
	s_cselect_b32 s9, s12, s38
	s_cselect_b32 s8, s13, s16
	v_lshl_add_u64 v[172:173], s[6:7], 0, v[148:149]
	s_add_i32 m0, s86, 0xc000
	ds_read_b128 v[168:171], v183
	ds_read_b128 v[190:193], v183 offset:1024
	ds_read_b128 v[194:197], v183 offset:2048
	ds_read_b128 v[198:201], v183 offset:3072
	ds_read_b128 v[202:205], v183 offset:4096
	ds_read_b128 v[206:209], v183 offset:5120
	ds_read_b128 v[210:213], v183 offset:6144
	ds_read_b128 v[214:217], v183 offset:7168
	global_load_lds_dwordx4 v[172:173], off
	v_lshl_add_u64 v[172:173], s[6:7], 0, v[150:151]
	s_add_i32 m0, s86, 0xe000
	s_nop 0
	global_load_lds_dwordx4 v[172:173], off
	s_waitcnt lgkmcnt(8)
	s_barrier
	s_waitcnt lgkmcnt(0)
	s_setprio 1
	s_waitcnt lgkmcnt(0)
	v_mfma_f32_16x16x32_bf16 v[126:129], v[130:133], v[168:171], v[126:129]
	v_mfma_f32_16x16x32_bf16 v[122:125], v[160:163], v[168:171], v[122:125]
	v_mfma_f32_16x16x32_bf16 v[110:113], v[130:133], v[194:197], v[110:113]
	v_mfma_f32_16x16x32_bf16 v[106:109], v[160:163], v[194:197], v[106:109]
	v_mfma_f32_16x16x32_bf16 v[94:97], v[130:133], v[202:205], v[94:97]
	v_mfma_f32_16x16x32_bf16 v[90:93], v[160:163], v[202:205], v[90:93]
	v_mfma_f32_16x16x32_bf16 v[78:81], v[130:133], v[210:213], v[78:81]
	v_mfma_f32_16x16x32_bf16 v[74:77], v[160:163], v[210:213], v[74:77]
	v_mfma_f32_16x16x32_bf16 v[126:129], v[156:159], v[190:193], v[126:129]
	v_mfma_f32_16x16x32_bf16 v[122:125], v[164:167], v[190:193], v[122:125]
	v_mfma_f32_16x16x32_bf16 v[110:113], v[156:159], v[198:201], v[110:113]
	v_mfma_f32_16x16x32_bf16 v[106:109], v[164:167], v[198:201], v[106:109]
	v_mfma_f32_16x16x32_bf16 v[94:97], v[156:159], v[206:209], v[94:97]
	v_mfma_f32_16x16x32_bf16 v[90:93], v[164:167], v[206:209], v[90:93]
	v_mfma_f32_16x16x32_bf16 v[78:81], v[156:159], v[214:217], v[78:81]
	v_mfma_f32_16x16x32_bf16 v[74:77], v[164:167], v[214:217], v[74:77]
	s_setprio 0
	s_barrier
	s_add_i32 s45, s31, s71
	v_lshl_add_u64 v[172:173], s[8:9], 0, v[134:135]
	s_mov_b32 m0, s45
	ds_read_b128 v[218:221], v184
	ds_read_b128 v[222:225], v184 offset:1024
	ds_read_b128 v[226:229], v184 offset:2048
	ds_read_b128 v[230:233], v184 offset:3072
	global_load_lds_dwordx4 v[172:173], off
	v_lshl_add_u64 v[234:235], s[8:9], 0, v[136:137]
	s_add_i32 m0, s45, 0x2000
	s_nop 0
	global_load_lds_dwordx4 v[234:235], off
	s_barrier
	s_waitcnt lgkmcnt(0)
	s_setprio 1
	s_waitcnt lgkmcnt(0)
	v_mfma_f32_16x16x32_bf16 v[118:121], v[218:221], v[168:171], v[118:121]
	v_mfma_f32_16x16x32_bf16 v[114:117], v[226:229], v[168:171], v[114:117]
	v_mfma_f32_16x16x32_bf16 v[102:105], v[218:221], v[194:197], v[102:105]
	v_mfma_f32_16x16x32_bf16 v[98:101], v[226:229], v[194:197], v[98:101]
	v_mfma_f32_16x16x32_bf16 v[86:89], v[218:221], v[202:205], v[86:89]
	v_mfma_f32_16x16x32_bf16 v[82:85], v[226:229], v[202:205], v[82:85]
	v_mfma_f32_16x16x32_bf16 v[70:73], v[218:221], v[210:213], v[70:73]
	v_mfma_f32_16x16x32_bf16 v[66:69], v[226:229], v[210:213], v[66:69]
	v_mfma_f32_16x16x32_bf16 v[118:121], v[222:225], v[190:193], v[118:121]
	v_mfma_f32_16x16x32_bf16 v[114:117], v[230:233], v[190:193], v[114:117]
	v_mfma_f32_16x16x32_bf16 v[102:105], v[222:225], v[198:201], v[102:105]
	v_mfma_f32_16x16x32_bf16 v[98:101], v[230:233], v[198:201], v[98:101]
	v_mfma_f32_16x16x32_bf16 v[86:89], v[222:225], v[206:209], v[86:89]
	v_mfma_f32_16x16x32_bf16 v[82:85], v[230:233], v[206:209], v[82:85]
	v_mfma_f32_16x16x32_bf16 v[70:73], v[222:225], v[214:217], v[70:73]
	v_mfma_f32_16x16x32_bf16 v[66:69], v[230:233], v[214:217], v[66:69]
	s_setprio 0
	s_mov_b32 m0, s86
	v_lshl_add_u64 v[236:237], s[10:11], 0, v[134:135]
	s_barrier
	ds_read_b128 v[168:171], v183 offset:16384
	ds_read_b128 v[190:193], v183 offset:17408
	ds_read_b128 v[194:197], v183 offset:18432
	ds_read_b128 v[198:201], v183 offset:19456
	ds_read_b128 v[202:205], v183 offset:20480
	ds_read_b128 v[206:209], v183 offset:21504
	ds_read_b128 v[210:213], v183 offset:22528
	ds_read_b128 v[214:217], v183 offset:23552
	global_load_lds_dwordx4 v[236:237], off
	v_lshl_add_u64 v[238:239], s[10:11], 0, v[136:137]
	s_mov_b32 m0, s87
	s_nop 0
	global_load_lds_dwordx4 v[238:239], off
	s_barrier
	s_waitcnt lgkmcnt(0)
	s_setprio 1
	s_waitcnt lgkmcnt(0)
	v_mfma_f32_16x16x32_bf16 v[62:65], v[130:133], v[168:171], v[62:65]
	v_mfma_f32_16x16x32_bf16 v[58:61], v[160:163], v[168:171], v[58:61]
	v_mfma_f32_16x16x32_bf16 v[46:49], v[130:133], v[194:197], v[46:49]
	v_mfma_f32_16x16x32_bf16 v[42:45], v[160:163], v[194:197], v[42:45]
	v_mfma_f32_16x16x32_bf16 v[30:33], v[130:133], v[202:205], v[30:33]
	v_mfma_f32_16x16x32_bf16 v[26:29], v[160:163], v[202:205], v[26:29]
	v_mfma_f32_16x16x32_bf16 v[14:17], v[130:133], v[210:213], v[14:17]
	v_mfma_f32_16x16x32_bf16 v[10:13], v[160:163], v[210:213], v[10:13]
	v_mfma_f32_16x16x32_bf16 v[62:65], v[156:159], v[190:193], v[62:65]
	v_mfma_f32_16x16x32_bf16 v[58:61], v[164:167], v[190:193], v[58:61]
	v_mfma_f32_16x16x32_bf16 v[46:49], v[156:159], v[198:201], v[46:49]
	v_mfma_f32_16x16x32_bf16 v[42:45], v[164:167], v[198:201], v[42:45]
	v_mfma_f32_16x16x32_bf16 v[30:33], v[156:159], v[206:209], v[30:33]
	v_mfma_f32_16x16x32_bf16 v[26:29], v[164:167], v[206:209], v[26:29]
	v_mfma_f32_16x16x32_bf16 v[14:17], v[156:159], v[214:217], v[14:17]
	v_mfma_f32_16x16x32_bf16 v[10:13], v[164:167], v[214:217], v[10:13]
	s_setprio 0
	s_barrier
	s_add_u32 s52, s8, 0x80000
	s_addc_u32 s53, s9, 0
	s_add_i32 s45, s36, s71
	v_lshl_add_u64 v[130:131], s[52:53], 0, v[134:135]
	s_mov_b32 m0, s45
	s_nop 0
	global_load_lds_dwordx4 v[130:131], off
	v_lshl_add_u64 v[130:131], s[52:53], 0, v[136:137]
	s_add_i32 m0, s45, 0x2000
	s_nop 0
	global_load_lds_dwordx4 v[130:131], off
	s_waitcnt vmcnt(6)
	s_barrier
	s_setprio 1
	v_mfma_f32_16x16x32_bf16 v[54:57], v[218:221], v[168:171], v[54:57]
	v_mfma_f32_16x16x32_bf16 v[50:53], v[226:229], v[168:171], v[50:53]
	v_mfma_f32_16x16x32_bf16 v[38:41], v[218:221], v[194:197], v[38:41]
	v_mfma_f32_16x16x32_bf16 v[34:37], v[226:229], v[194:197], v[34:37]
	v_mfma_f32_16x16x32_bf16 v[22:25], v[218:221], v[202:205], v[22:25]
	v_mfma_f32_16x16x32_bf16 v[18:21], v[226:229], v[202:205], v[18:21]
	v_mfma_f32_16x16x32_bf16 v[6:9], v[218:221], v[210:213], v[6:9]
	v_mfma_f32_16x16x32_bf16 v[2:5], v[226:229], v[210:213], v[2:5]
	v_mfma_f32_16x16x32_bf16 v[54:57], v[222:225], v[190:193], v[54:57]
	v_mfma_f32_16x16x32_bf16 v[50:53], v[230:233], v[190:193], v[50:53]
	v_mfma_f32_16x16x32_bf16 v[38:41], v[222:225], v[198:201], v[38:41]
	v_mfma_f32_16x16x32_bf16 v[34:37], v[230:233], v[198:201], v[34:37]
	v_mfma_f32_16x16x32_bf16 v[22:25], v[222:225], v[206:209], v[22:25]
	v_mfma_f32_16x16x32_bf16 v[18:21], v[230:233], v[206:209], v[18:21]
	v_mfma_f32_16x16x32_bf16 v[6:9], v[222:225], v[214:217], v[6:9]
	v_mfma_f32_16x16x32_bf16 v[2:5], v[230:233], v[214:217], v[2:5]
	s_setprio 0
	s_add_i32 s45, 0, 0x18000
	v_add_u32_e32 v138, s45, v141
	s_barrier
	ds_read_b128 v[130:133], v138
	ds_read_b128 v[156:159], v138 offset:1024
	ds_read_b128 v[160:163], v138 offset:2048
	ds_read_b128 v[164:167], v138 offset:3072
	s_add_u32 s10, s10, 0x80000
	s_addc_u32 s11, s11, 0
	s_mov_b32 m0, s96
	v_lshl_add_u64 v[218:219], s[10:11], 0, v[134:135]
	ds_read_b128 v[168:171], v183 offset:32768
	ds_read_b128 v[190:193], v183 offset:33792
	ds_read_b128 v[194:197], v183 offset:34816
	ds_read_b128 v[198:201], v183 offset:35840
	ds_read_b128 v[202:205], v183 offset:36864
	ds_read_b128 v[206:209], v183 offset:37888
	ds_read_b128 v[210:213], v183 offset:38912
	ds_read_b128 v[214:217], v183 offset:39936
	global_load_lds_dwordx4 v[218:219], off
	v_lshl_add_u64 v[218:219], s[10:11], 0, v[136:137]
	s_mov_b32 m0, s97
	s_nop 0
	global_load_lds_dwordx4 v[218:219], off
	s_waitcnt lgkmcnt(8)
	s_barrier
	s_waitcnt lgkmcnt(0)
	s_setprio 1
	s_waitcnt lgkmcnt(0)
	v_mfma_f32_16x16x32_bf16 v[126:129], v[130:133], v[168:171], v[126:129]
	v_mfma_f32_16x16x32_bf16 v[122:125], v[160:163], v[168:171], v[122:125]
	v_mfma_f32_16x16x32_bf16 v[110:113], v[130:133], v[194:197], v[110:113]
	v_mfma_f32_16x16x32_bf16 v[106:109], v[160:163], v[194:197], v[106:109]
	v_mfma_f32_16x16x32_bf16 v[94:97], v[130:133], v[202:205], v[94:97]
	v_mfma_f32_16x16x32_bf16 v[90:93], v[160:163], v[202:205], v[90:93]
	v_mfma_f32_16x16x32_bf16 v[78:81], v[130:133], v[210:213], v[78:81]
	v_mfma_f32_16x16x32_bf16 v[74:77], v[160:163], v[210:213], v[74:77]
	v_mfma_f32_16x16x32_bf16 v[126:129], v[156:159], v[190:193], v[126:129]
	v_mfma_f32_16x16x32_bf16 v[122:125], v[164:167], v[190:193], v[122:125]
	v_mfma_f32_16x16x32_bf16 v[110:113], v[156:159], v[198:201], v[110:113]
	v_mfma_f32_16x16x32_bf16 v[106:109], v[164:167], v[198:201], v[106:109]
	v_mfma_f32_16x16x32_bf16 v[94:97], v[156:159], v[206:209], v[94:97]
	v_mfma_f32_16x16x32_bf16 v[90:93], v[164:167], v[206:209], v[90:93]
	v_mfma_f32_16x16x32_bf16 v[78:81], v[156:159], v[214:217], v[78:81]
	v_mfma_f32_16x16x32_bf16 v[74:77], v[164:167], v[214:217], v[74:77]
	s_setprio 0
	s_barrier
	s_add_i32 s10, 0, 0x1c000
	s_add_i32 s11, s45, s71
	v_add_u32_e32 v138, s10, v141
	v_lshl_add_u64 v[172:173], v[172:173], 0, s[26:27]
	s_mov_b32 m0, s11
	ds_read_b128 v[218:221], v138
	ds_read_b128 v[222:225], v138 offset:1024
	ds_read_b128 v[226:229], v138 offset:2048
	ds_read_b128 v[230:233], v138 offset:3072
	global_load_lds_dwordx4 v[172:173], off
	v_lshl_add_u64 v[172:173], v[234:235], 0, s[26:27]
	s_add_i32 m0, s11, 0x2000
	s_nop 0
	global_load_lds_dwordx4 v[172:173], off
	s_barrier
	s_waitcnt lgkmcnt(0)
	s_setprio 1
	s_waitcnt lgkmcnt(0)
	v_mfma_f32_16x16x32_bf16 v[118:121], v[218:221], v[168:171], v[118:121]
	v_mfma_f32_16x16x32_bf16 v[114:117], v[226:229], v[168:171], v[114:117]
	v_mfma_f32_16x16x32_bf16 v[102:105], v[218:221], v[194:197], v[102:105]
	v_mfma_f32_16x16x32_bf16 v[98:101], v[226:229], v[194:197], v[98:101]
	v_mfma_f32_16x16x32_bf16 v[86:89], v[218:221], v[202:205], v[86:89]
	v_mfma_f32_16x16x32_bf16 v[82:85], v[226:229], v[202:205], v[82:85]
	v_mfma_f32_16x16x32_bf16 v[70:73], v[218:221], v[210:213], v[70:73]
	v_mfma_f32_16x16x32_bf16 v[66:69], v[226:229], v[210:213], v[66:69]
	v_mfma_f32_16x16x32_bf16 v[118:121], v[222:225], v[190:193], v[118:121]
	v_mfma_f32_16x16x32_bf16 v[114:117], v[230:233], v[190:193], v[114:117]
	v_mfma_f32_16x16x32_bf16 v[102:105], v[222:225], v[198:201], v[102:105]
	v_mfma_f32_16x16x32_bf16 v[98:101], v[230:233], v[198:201], v[98:101]
	v_mfma_f32_16x16x32_bf16 v[86:89], v[222:225], v[206:209], v[86:89]
	v_mfma_f32_16x16x32_bf16 v[82:85], v[230:233], v[206:209], v[82:85]
	v_mfma_f32_16x16x32_bf16 v[70:73], v[222:225], v[214:217], v[70:73]
	v_mfma_f32_16x16x32_bf16 v[66:69], v[230:233], v[214:217], v[66:69]
	s_setprio 0
	s_mov_b32 m0, s14
	v_lshl_add_u64 v[172:173], v[236:237], 0, s[26:27]
	s_barrier
	ds_read_b128 v[168:171], v183 offset:49152
	ds_read_b128 v[190:193], v183 offset:50176
	ds_read_b128 v[194:197], v183 offset:51200
	ds_read_b128 v[198:201], v183 offset:52224
	ds_read_b128 v[202:205], v183 offset:53248
	ds_read_b128 v[206:209], v183 offset:54272
	ds_read_b128 v[210:213], v183 offset:55296
	ds_read_b128 v[214:217], v183 offset:56320
	global_load_lds_dwordx4 v[172:173], off
	v_lshl_add_u64 v[172:173], v[238:239], 0, s[26:27]
	s_mov_b32 m0, s15
	s_nop 0
	global_load_lds_dwordx4 v[172:173], off
	s_barrier
	s_waitcnt lgkmcnt(0)
	s_setprio 1
	s_waitcnt lgkmcnt(0)
	v_mfma_f32_16x16x32_bf16 v[62:65], v[130:133], v[168:171], v[62:65]
	v_mfma_f32_16x16x32_bf16 v[58:61], v[160:163], v[168:171], v[58:61]
	v_mfma_f32_16x16x32_bf16 v[46:49], v[130:133], v[194:197], v[46:49]
	v_mfma_f32_16x16x32_bf16 v[42:45], v[160:163], v[194:197], v[42:45]
	v_mfma_f32_16x16x32_bf16 v[30:33], v[130:133], v[202:205], v[30:33]
	v_mfma_f32_16x16x32_bf16 v[26:29], v[160:163], v[202:205], v[26:29]
	v_mfma_f32_16x16x32_bf16 v[14:17], v[130:133], v[210:213], v[14:17]
	v_mfma_f32_16x16x32_bf16 v[10:13], v[160:163], v[210:213], v[10:13]
	v_mfma_f32_16x16x32_bf16 v[62:65], v[156:159], v[190:193], v[62:65]
	v_mfma_f32_16x16x32_bf16 v[58:61], v[164:167], v[190:193], v[58:61]
	v_mfma_f32_16x16x32_bf16 v[46:49], v[156:159], v[198:201], v[46:49]
	v_mfma_f32_16x16x32_bf16 v[42:45], v[164:167], v[198:201], v[42:45]
	v_mfma_f32_16x16x32_bf16 v[30:33], v[156:159], v[206:209], v[30:33]
	v_mfma_f32_16x16x32_bf16 v[26:29], v[164:167], v[206:209], v[26:29]
	v_mfma_f32_16x16x32_bf16 v[14:17], v[156:159], v[214:217], v[14:17]
	v_mfma_f32_16x16x32_bf16 v[10:13], v[164:167], v[214:217], v[10:13]
	s_setprio 0
	s_barrier
	s_add_u32 s8, s8, 0x80080
	s_addc_u32 s9, s9, 0
	s_add_i32 s10, s10, s71
	v_lshl_add_u64 v[130:131], s[8:9], 0, v[134:135]
	s_mov_b32 m0, s10
	s_nop 0
	global_load_lds_dwordx4 v[130:131], off
	v_lshl_add_u64 v[130:131], s[8:9], 0, v[136:137]
	s_add_i32 m0, s10, 0x2000
	s_nop 0
	global_load_lds_dwordx4 v[130:131], off
	s_waitcnt vmcnt(6)
	s_barrier
	s_setprio 1
	v_mfma_f32_16x16x32_bf16 v[54:57], v[218:221], v[168:171], v[54:57]
	v_mfma_f32_16x16x32_bf16 v[50:53], v[226:229], v[168:171], v[50:53]
	v_mfma_f32_16x16x32_bf16 v[38:41], v[218:221], v[194:197], v[38:41]
	v_mfma_f32_16x16x32_bf16 v[34:37], v[226:229], v[194:197], v[34:37]
	v_mfma_f32_16x16x32_bf16 v[22:25], v[218:221], v[202:205], v[22:25]
	v_mfma_f32_16x16x32_bf16 v[18:21], v[226:229], v[202:205], v[18:21]
	v_mfma_f32_16x16x32_bf16 v[6:9], v[218:221], v[210:213], v[6:9]
	v_mfma_f32_16x16x32_bf16 v[2:5], v[226:229], v[210:213], v[2:5]
	v_mfma_f32_16x16x32_bf16 v[54:57], v[222:225], v[190:193], v[54:57]
	v_mfma_f32_16x16x32_bf16 v[50:53], v[230:233], v[190:193], v[50:53]
	v_mfma_f32_16x16x32_bf16 v[38:41], v[222:225], v[198:201], v[38:41]
	v_mfma_f32_16x16x32_bf16 v[34:37], v[230:233], v[198:201], v[34:37]
	v_mfma_f32_16x16x32_bf16 v[22:25], v[222:225], v[206:209], v[22:25]
	v_mfma_f32_16x16x32_bf16 v[18:21], v[230:233], v[206:209], v[18:21]
	v_mfma_f32_16x16x32_bf16 v[6:9], v[222:225], v[214:217], v[6:9]
	v_mfma_f32_16x16x32_bf16 v[2:5], v[230:233], v[214:217], v[2:5]
	s_setprio 0
	s_add_i32 s39, s39, 2
	s_add_u32 s6, s6, 0x100
	s_addc_u32 s7, s7, 0
	s_add_u32 s16, s16, 0x100
	s_addc_u32 s38, s38, 0
	s_cmp_gt_u32 s39, 29
	s_barrier
	s_cbranch_scc0 .LBB0_342
	s_add_i32 s62, s2, -4
	s_and_b32 s63, s2, 1
	s_lshr_b32 s64, s62, 1
	s_cmp_eq_u32 s63, 0
	s_cselect_b64 s[12:13], -1, 0
	s_cmp_gt_i32 s62, 1
	s_cselect_b64 s[62:63], -1, 0
	s_and_b64 s[12:13], s[12:13], s[62:63]
	s_cmp_lt_u32 s64, 3
	s_cselect_b64 s[62:63], -1, 0
	s_lshl_b32 s64, s64, 6
	s_and_b64 s[12:13], s[12:13], s[62:63]
	s_mov_b32 s65, 0
	v_lshl_add_u64 v[196:197], s[64:65], 2, v[144:145]
	v_cndmask_b32_e64 v196, v146, v196, s[12:13]
	v_cndmask_b32_e64 v197, v147, v197, s[12:13]
	global_load_dwordx4 v[200:203], v[196:197], off
	global_load_dwordx4 v[204:207], v[196:197], off offset:64
	global_load_dwordx4 v[208:211], v[196:197], off offset:128
	global_load_dwordx4 v[212:215], v[196:197], off offset:192
	v_and_b32_e32 v131, 64, v185
	v_xor_b32_e32 v130, 16, v185
	v_add_u32_e32 v131, 64, v131
	v_cmp_lt_i32_e32 vcc, v130, v131
	s_cmp_gt_i32 s0, 63
	s_cselect_b64 s[6:7], -1, 0
	v_cndmask_b32_e32 v130, v185, v130, vcc
	v_lshlrev_b32_e32 v189, 2, v130
	v_xor_b32_e32 v130, 32, v185
	v_cmp_lt_i32_e32 vcc, v130, v131
	s_cmp_lt_i32 s0, 64
	s_cselect_b64 s[52:53], -1, 0
	v_cndmask_b32_e32 v130, v185, v130, vcc
	v_lshlrev_b32_e32 v190, 2, v130
	v_mul_f32_e32 v130, v127, v127
	v_fmac_f32_e32 v130, v126, v126
	v_fmac_f32_e32 v130, v128, v128
	v_fmac_f32_e32 v130, v129, v129
	v_fmac_f32_e32 v130, v122, v122
	v_fmac_f32_e32 v130, v123, v123
	v_fmac_f32_e32 v130, v124, v124
	v_fmac_f32_e32 v130, v125, v125
	v_fmac_f32_e32 v130, v118, v118
	v_fmac_f32_e32 v130, v119, v119
	v_fmac_f32_e32 v130, v120, v120
	v_fmac_f32_e32 v130, v121, v121
	v_fmac_f32_e32 v130, v114, v114
	v_fmac_f32_e32 v130, v115, v115
	v_fmac_f32_e32 v130, v116, v116
	v_fmac_f32_e32 v130, v117, v117
	ds_bpermute_b32 v131, v189, v130
	s_cmp_gt_i32 s2, 3
	s_cselect_b64 s[10:11], -1, 0
	s_cmp_gt_u32 s2, 9
	s_cselect_b64 s[12:13], -1, 0
	s_waitcnt lgkmcnt(0)
	v_add_f32_e32 v130, v130, v131
	s_cmp_lg_u32 s2, 10
	ds_bpermute_b32 v131, v190, v130
	s_cselect_b64 s[60:61], -1, 0
	s_add_i32 s1, s2, -4
	s_lshl_b32 s39, s2, 8
	s_lshr_b32 s8, s1, 1
	s_and_b32 s9, s2, 1
	s_cmp_eq_u32 s9, 0
	s_cselect_b64 s[2:3], -1, 0
	s_cmp_gt_u32 s1, 1
	s_cselect_b64 s[54:55], -1, 0
	s_lshl_b32 s1, s9, 8
	s_waitcnt lgkmcnt(0)
	v_add_f32_e32 v130, v130, v131
	s_and_b64 s[58:59], s[2:3], s[54:55]
	s_or_b32 s45, s1, s34
	s_lshl_b32 s16, s8, 6
	v_fmamk_f32 v130, v130, 0x3c800000, v188
	s_cmp_lg_u32 s8, 1
	v_rsq_f32_e32 v158, v130
	s_cselect_b64 s[56:57], -1, 0
	s_lshl_b32 s47, s0, 8
	v_readlane_b32 s0, v253, 42
	s_add_i32 s47, s47, s0
	v_add_u32_e32 v138, s39, v175
	v_or_b32_e32 v156, s47, v1
	s_ashr_i32 s38, s47, 11
	s_mov_b64 s[0:1], -1
	s_waitcnt vmcnt(0)
	s_and_b64 vcc, exec, s[10:11]
	s_cbranch_vccz .LBB0_429
	v_add_u32_e32 v164, 0xffffc000, v156
	v_and_b32_e32 v131, 0x7cf, v156
	v_ashrrev_i32_e32 v130, 3, v164
	v_cndmask_b32_e64 v165, v131, v174, s[6:7]
	v_mov_b32_e32 v131, s38
	v_cndmask_b32_e64 v162, v131, v130, s[6:7]
	s_and_b64 vcc, exec, s[12:13]
	s_cbranch_vccz .LBB0_359
	s_andn2_b64 vcc, exec, s[60:61]
	s_cbranch_vccnz .LBB0_355
	v_add_u32_e32 v132, 7, v165
	v_mov_b32_e32 v133, v139
	v_mad_i64_i32 v[132:133], s[0:1], v162, 15, v[132:133]
	v_ashrrev_i32_e32 v157, 31, v156
	v_readlane_b32 s0, v253, 43
	v_lshlrev_b64 v[130:131], 11, v[156:157]
	v_lshlrev_b64 v[132:133], 12, v[132:133]
	v_readlane_b32 s1, v253, 44
	v_lshl_add_u64 v[130:131], s[24:25], 0, v[130:131]
	v_lshl_add_u64 v[130:131], v[138:139], 1, v[130:131]
	v_lshl_add_u64 v[132:133], s[0:1], 0, v[132:133]
	v_cvt_pk_bf16_f32 v160, v126, v127
	v_cvt_pk_bf16_f32 v161, v128, v129
	s_and_b64 vcc, exec, s[6:7]
	v_lshl_add_u64 v[132:133], v[138:139], 2, v[132:133]
	global_store_dwordx2 v[130:131], v[160:161], off
	s_cbranch_vccz .LBB0_348
	global_store_dwordx4 v[132:133], v[126:129], off

.LBB0_359:
	s_andn2_b64 vcc, exec, s[0:1]
	s_cbranch_vccnz .LBB0_428
	v_cndmask_b32_e64 v130, 0, 1, s[58:59]
	v_cmp_ne_u32_e64 s[2:3], 1, v130
	v_mov_b64_e32 v[132:133], v[128:129]
	v_mov_b32_e32 v159, v158
	s_andn2_b64 vcc, exec, s[58:59]
	v_mov_b64_e32 v[130:131], v[126:127]
	s_cbranch_vccnz .LBB0_362
	v_lshl_add_u64 v[130:131], s[16:17], 2, v[144:145]
	v_mov_b32_e32 v160, v158
	v_mov_b32_e32 v161, v158
	v_pk_mul_f32 v[166:167], v[126:127], v[158:159]
	v_pk_mul_f32 v[160:161], v[128:129], v[160:161]
	v_pk_mul_f32 v[130:131], v[166:167], v[200:201]
	v_pk_mul_f32 v[132:133], v[160:161], v[202:203]

.LBB0_377:
	s_nop 1
	v_mov_b64_e32 v[132:133], v[124:125]
	s_and_b64 vcc, exec, s[2:3]
	v_mov_b64_e32 v[130:131], v[122:123]
	s_cbranch_vccnz .LBB0_379
	v_lshl_add_u64 v[130:131], s[16:17], 2, v[144:145]
	v_mov_b32_e32 v172, v158
	v_mov_b32_e32 v173, v158
	v_pk_mul_f32 v[192:193], v[122:123], v[158:159]
	v_pk_mul_f32 v[172:173], v[124:125], v[172:173]
	v_pk_mul_f32 v[130:131], v[192:193], v[204:205]
	v_pk_mul_f32 v[132:133], v[172:173], v[206:207]

.LBB0_393:
	v_lshl_add_u64 v[130:131], s[16:17], 2, v[144:145]
	v_mov_b32_e32 v172, v158
	v_mov_b32_e32 v173, v158
	v_pk_mul_f32 v[192:193], v[118:119], v[158:159]
	v_pk_mul_f32 v[172:173], v[120:121], v[172:173]
	v_pk_mul_f32 v[130:131], v[192:193], v[208:209]
	v_pk_mul_f32 v[132:133], v[172:173], v[210:211]
	s_and_b64 vcc, exec, s[8:9]
	s_mov_b64 s[62:63], -1
	s_cbranch_vccz .LBB0_412

.LBB0_425:
	v_lshl_add_u64 v[130:131], s[16:17], 2, v[144:145]
	v_mov_b32_e32 v172, v158
	v_mov_b32_e32 v173, v158
	v_pk_mul_f32 v[192:193], v[114:115], v[158:159]
	v_pk_mul_f32 v[172:173], v[116:117], v[172:173]
	v_pk_mul_f32 v[130:131], v[192:193], v[212:213]
	v_pk_mul_f32 v[132:133], v[172:173], v[214:215]
	s_and_b64 vcc, exec, s[8:9]
	s_mov_b64 s[2:3], -1
	s_cbranch_vccz .LBB0_397

.LBB0_429:
	s_or_b32 s62, s39, s34
	s_ashr_i32 s63, s62, 31
	s_andn2_b64 vcc, exec, s[0:1]
	v_lshlrev_b32_e32 v130, 1, v140
	s_cbranch_vccnz .LBB0_431
	v_ashrrev_i32_e32 v157, 31, v156
	v_lshlrev_b64 v[132:133], 11, v[156:157]
	v_mul_f32_e32 v156, 0x3e38aa3b, v158
	v_pk_mul_f32 v[158:159], v[128:129], v[156:157] op_sel_hi:[1,0]
	v_pk_mul_f32 v[160:161], v[126:127], v[156:157] op_sel_hi:[1,0]
	v_lshl_add_u64 v[132:133], s[18:19], 0, v[132:133]
	v_lshl_add_u64 v[132:133], s[62:63], 1, v[132:133]
	v_mov_b32_e32 v131, v139
	v_lshl_add_u64 v[132:133], v[132:133], 0, v[130:131]
	v_pk_mul_f32 v[128:129], v[158:159], v[202:203]
	v_pk_mul_f32 v[126:127], v[160:161], v[200:201]
	s_nop 0
	v_cvt_pk_bf16_f32 v126, v126, v127
	v_cvt_pk_bf16_f32 v127, v128, v129
	global_store_dwordx2 v[132:133], v[126:127], off
	v_pk_mul_f32 v[126:127], v[124:125], v[156:157] op_sel_hi:[1,0]
	v_pk_mul_f32 v[128:129], v[122:123], v[156:157] op_sel_hi:[1,0]
	v_pk_mul_f32 v[124:125], v[126:127], v[206:207]
	v_pk_mul_f32 v[122:123], v[128:129], v[204:205]
	s_nop 0
	v_cvt_pk_bf16_f32 v122, v122, v123
	v_cvt_pk_bf16_f32 v123, v124, v125
	global_store_dwordx2 v[132:133], v[122:123], off offset:32
	v_pk_mul_f32 v[122:123], v[120:121], v[156:157] op_sel_hi:[1,0]
	v_pk_mul_f32 v[124:125], v[118:119], v[156:157] op_sel_hi:[1,0]
	v_pk_mul_f32 v[120:121], v[122:123], v[210:211]
	v_pk_mul_f32 v[118:119], v[124:125], v[208:209]
	s_nop 0
	v_cvt_pk_bf16_f32 v118, v118, v119
	v_cvt_pk_bf16_f32 v119, v120, v121
	global_store_dwordx2 v[132:133], v[118:119], off offset:64
	v_pk_mul_f32 v[118:119], v[116:117], v[156:157] op_sel_hi:[1,0]
	v_pk_mul_f32 v[120:121], v[114:115], v[156:157] op_sel_hi:[1,0]
	v_pk_mul_f32 v[116:117], v[118:119], v[214:215]
	v_pk_mul_f32 v[114:115], v[120:121], v[212:213]
	s_nop 0
	v_cvt_pk_bf16_f32 v114, v114, v115
	v_cvt_pk_bf16_f32 v115, v116, v117
	global_store_dwordx2 v[132:133], v[114:115], off offset:96

.LBB0_447:
	s_andn2_b64 vcc, exec, s[8:9]
	s_cbranch_vccnz .LBB0_516
	v_cndmask_b32_e64 v114, 0, 1, s[58:59]
	v_cmp_ne_u32_e64 s[10:11], 1, v114
	v_mov_b64_e32 v[116:117], v[112:113]
	v_mov_b32_e32 v121, v120
	s_andn2_b64 vcc, exec, s[58:59]
	v_mov_b64_e32 v[114:115], v[110:111]
	s_cbranch_vccnz .LBB0_450
	v_lshl_add_u64 v[114:115], s[16:17], 2, v[144:145]
	v_mov_b32_e32 v122, v120
	v_mov_b32_e32 v123, v120
	v_pk_mul_f32 v[128:129], v[110:111], v[120:121]
	v_pk_mul_f32 v[122:123], v[112:113], v[122:123]
	v_pk_mul_f32 v[114:115], v[128:129], v[200:201]
	v_pk_mul_f32 v[116:117], v[122:123], v[202:203]

.LBB0_479:
	v_lshl_add_u64 v[114:115], s[16:17], 2, v[144:145]
	v_mov_b32_e32 v158, v120
	v_mov_b32_e32 v159, v120
	v_pk_mul_f32 v[160:161], v[102:103], v[120:121]
	v_pk_mul_f32 v[158:159], v[104:105], v[158:159]
	v_pk_mul_f32 v[114:115], v[160:161], v[208:209]
	v_pk_mul_f32 v[116:117], v[158:159], v[210:211]
	s_and_b64 vcc, exec, s[12:13]
	s_mov_b64 s[64:65], -1
	s_cbranch_vccz .LBB0_500

.LBB0_496:
	v_lshl_add_u64 v[114:115], s[16:17], 2, v[144:145]
	v_mov_b32_e32 v158, v120
	v_mov_b32_e32 v159, v120
	v_pk_mul_f32 v[160:161], v[106:107], v[120:121]
	v_pk_mul_f32 v[158:159], v[108:109], v[158:159]
	v_pk_mul_f32 v[114:115], v[160:161], v[204:205]
	v_pk_mul_f32 v[116:117], v[158:159], v[206:207]
	s_and_b64 vcc, exec, s[12:13]
	s_mov_b64 s[64:65], -1
	s_cbranch_vccz .LBB0_466

.LBB0_513:
	v_lshl_add_u64 v[114:115], s[16:17], 2, v[144:145]
	v_mov_b32_e32 v158, v120
	v_mov_b32_e32 v159, v120
	v_pk_mul_f32 v[160:161], v[98:99], v[120:121]
	v_pk_mul_f32 v[158:159], v[100:101], v[158:159]
	v_pk_mul_f32 v[114:115], v[160:161], v[212:213]
	v_pk_mul_f32 v[116:117], v[158:159], v[214:215]
	s_and_b64 vcc, exec, s[12:13]
	s_mov_b64 s[10:11], -1
	s_cbranch_vccz .LBB0_483

.LBB0_517:
	s_andn2_b64 vcc, exec, s[8:9]
	s_cbranch_vccnz .LBB0_519
	v_ashrrev_i32_e32 v119, 31, v118
	v_mul_f32_e32 v116, 0x3e38aa3b, v120
	v_lshlrev_b64 v[114:115], 11, v[118:119]
	v_pk_mul_f32 v[118:119], v[112:113], v[116:117] op_sel_hi:[1,0]
	v_pk_mul_f32 v[120:121], v[110:111], v[116:117] op_sel_hi:[1,0]
	v_lshl_add_u64 v[114:115], s[18:19], 0, v[114:115]
	v_lshl_add_u64 v[114:115], s[62:63], 1, v[114:115]
	v_mov_b32_e32 v131, v139
	v_lshl_add_u64 v[114:115], v[114:115], 0, v[130:131]
	v_pk_mul_f32 v[112:113], v[118:119], v[202:203]
	v_pk_mul_f32 v[110:111], v[120:121], v[200:201]
	s_nop 0
	v_cvt_pk_bf16_f32 v110, v110, v111
	v_cvt_pk_bf16_f32 v111, v112, v113
	global_store_dwordx2 v[114:115], v[110:111], off
	v_pk_mul_f32 v[110:111], v[108:109], v[116:117] op_sel_hi:[1,0]
	v_pk_mul_f32 v[112:113], v[106:107], v[116:117] op_sel_hi:[1,0]
	v_pk_mul_f32 v[108:109], v[110:111], v[206:207]
	v_pk_mul_f32 v[106:107], v[112:113], v[204:205]
	s_nop 0
	v_cvt_pk_bf16_f32 v106, v106, v107
	v_cvt_pk_bf16_f32 v107, v108, v109
	global_store_dwordx2 v[114:115], v[106:107], off offset:32
	v_pk_mul_f32 v[106:107], v[104:105], v[116:117] op_sel_hi:[1,0]
	v_pk_mul_f32 v[108:109], v[102:103], v[116:117] op_sel_hi:[1,0]
	v_pk_mul_f32 v[104:105], v[106:107], v[210:211]
	v_pk_mul_f32 v[102:103], v[108:109], v[208:209]
	s_nop 0
	v_cvt_pk_bf16_f32 v102, v102, v103
	v_cvt_pk_bf16_f32 v103, v104, v105
	global_store_dwordx2 v[114:115], v[102:103], off offset:64
	v_pk_mul_f32 v[102:103], v[100:101], v[116:117] op_sel_hi:[1,0]
	v_pk_mul_f32 v[104:105], v[98:99], v[116:117] op_sel_hi:[1,0]
	v_pk_mul_f32 v[100:101], v[102:103], v[214:215]
	v_pk_mul_f32 v[98:99], v[104:105], v[212:213]
	s_nop 0
	v_cvt_pk_bf16_f32 v98, v98, v99
	v_cvt_pk_bf16_f32 v99, v100, v101
	global_store_dwordx2 v[114:115], v[98:99], off offset:96

.LBB0_535:
	s_andn2_b64 vcc, exec, s[8:9]
	s_cbranch_vccnz .LBB0_604
	v_cndmask_b32_e64 v98, 0, 1, s[58:59]
	v_cmp_ne_u32_e64 s[10:11], 1, v98
	v_mov_b64_e32 v[100:101], v[96:97]
	v_mov_b32_e32 v103, v102
	s_andn2_b64 vcc, exec, s[58:59]
	v_mov_b64_e32 v[98:99], v[94:95]
	s_cbranch_vccnz .LBB0_538
	v_lshl_add_u64 v[98:99], s[16:17], 2, v[144:145]
	v_mov_b32_e32 v106, v102
	v_mov_b32_e32 v107, v102
	v_pk_mul_f32 v[112:113], v[94:95], v[102:103]
	v_pk_mul_f32 v[106:107], v[96:97], v[106:107]
	v_pk_mul_f32 v[98:99], v[112:113], v[200:201]
	v_pk_mul_f32 v[100:101], v[106:107], v[202:203]

.LBB0_567:
	v_lshl_add_u64 v[98:99], s[16:17], 2, v[144:145]
	v_mov_b32_e32 v118, v102
	v_mov_b32_e32 v119, v102
	v_pk_mul_f32 v[122:123], v[86:87], v[102:103]
	v_pk_mul_f32 v[118:119], v[88:89], v[118:119]
	v_pk_mul_f32 v[98:99], v[122:123], v[208:209]
	v_pk_mul_f32 v[100:101], v[118:119], v[210:211]
	s_and_b64 vcc, exec, s[12:13]
	s_mov_b64 s[64:65], -1
	s_cbranch_vccz .LBB0_588

.LBB0_584:
	v_lshl_add_u64 v[98:99], s[16:17], 2, v[144:145]
	v_mov_b32_e32 v118, v102
	v_mov_b32_e32 v119, v102
	v_pk_mul_f32 v[122:123], v[90:91], v[102:103]
	v_pk_mul_f32 v[118:119], v[92:93], v[118:119]
	v_pk_mul_f32 v[98:99], v[122:123], v[204:205]
	v_pk_mul_f32 v[100:101], v[118:119], v[206:207]
	s_and_b64 vcc, exec, s[12:13]
	s_mov_b64 s[64:65], -1
	s_cbranch_vccz .LBB0_554

.LBB0_601:
	v_lshl_add_u64 v[98:99], s[16:17], 2, v[144:145]
	v_mov_b32_e32 v118, v102
	v_mov_b32_e32 v119, v102
	v_pk_mul_f32 v[122:123], v[82:83], v[102:103]
	v_pk_mul_f32 v[118:119], v[84:85], v[118:119]
	v_pk_mul_f32 v[98:99], v[122:123], v[212:213]
	v_pk_mul_f32 v[100:101], v[118:119], v[214:215]
	s_and_b64 vcc, exec, s[12:13]
	s_mov_b64 s[10:11], -1
	s_cbranch_vccz .LBB0_571

.LBB0_605:
	s_andn2_b64 vcc, exec, s[8:9]
	s_cbranch_vccnz .LBB0_607
	v_ashrrev_i32_e32 v105, 31, v104
	v_mul_f32_e32 v100, 0x3e38aa3b, v102
	v_lshlrev_b64 v[98:99], 11, v[104:105]
	v_pk_mul_f32 v[102:103], v[96:97], v[100:101] op_sel_hi:[1,0]
	v_pk_mul_f32 v[104:105], v[94:95], v[100:101] op_sel_hi:[1,0]
	v_lshl_add_u64 v[98:99], s[18:19], 0, v[98:99]
	v_lshl_add_u64 v[98:99], s[62:63], 1, v[98:99]
	v_mov_b32_e32 v131, v139
	v_lshl_add_u64 v[98:99], v[98:99], 0, v[130:131]
	v_pk_mul_f32 v[96:97], v[102:103], v[202:203]
	v_pk_mul_f32 v[94:95], v[104:105], v[200:201]
	s_nop 0
	v_cvt_pk_bf16_f32 v94, v94, v95
	v_cvt_pk_bf16_f32 v95, v96, v97
	global_store_dwordx2 v[98:99], v[94:95], off
	v_pk_mul_f32 v[94:95], v[92:93], v[100:101] op_sel_hi:[1,0]
	v_pk_mul_f32 v[96:97], v[90:91], v[100:101] op_sel_hi:[1,0]
	v_pk_mul_f32 v[92:93], v[94:95], v[206:207]
	v_pk_mul_f32 v[90:91], v[96:97], v[204:205]
	s_nop 0
	v_cvt_pk_bf16_f32 v90, v90, v91
	v_cvt_pk_bf16_f32 v91, v92, v93
	global_store_dwordx2 v[98:99], v[90:91], off offset:32
	v_pk_mul_f32 v[90:91], v[88:89], v[100:101] op_sel_hi:[1,0]
	v_pk_mul_f32 v[92:93], v[86:87], v[100:101] op_sel_hi:[1,0]
	v_pk_mul_f32 v[88:89], v[90:91], v[210:211]
	v_pk_mul_f32 v[86:87], v[92:93], v[208:209]
	s_nop 0
	v_cvt_pk_bf16_f32 v86, v86, v87
	v_cvt_pk_bf16_f32 v87, v88, v89
	global_store_dwordx2 v[98:99], v[86:87], off offset:64
	v_pk_mul_f32 v[86:87], v[84:85], v[100:101] op_sel_hi:[1,0]
	v_pk_mul_f32 v[88:89], v[82:83], v[100:101] op_sel_hi:[1,0]
	v_pk_mul_f32 v[84:85], v[86:87], v[214:215]
	v_pk_mul_f32 v[82:83], v[88:89], v[212:213]
	s_nop 0
	v_cvt_pk_bf16_f32 v82, v82, v83
	v_cvt_pk_bf16_f32 v83, v84, v85
	global_store_dwordx2 v[98:99], v[82:83], off offset:96

.LBB0_623:
	s_andn2_b64 vcc, exec, s[8:9]
	s_cbranch_vccnz .LBB0_692
	v_cndmask_b32_e64 v82, 0, 1, s[58:59]
	v_cmp_ne_u32_e64 s[10:11], 1, v82
	v_mov_b64_e32 v[84:85], v[80:81]
	v_mov_b32_e32 v87, v86
	s_andn2_b64 vcc, exec, s[58:59]
	v_mov_b64_e32 v[82:83], v[78:79]
	s_cbranch_vccnz .LBB0_626
	v_lshl_add_u64 v[82:83], s[16:17], 2, v[144:145]
	v_mov_b32_e32 v90, v86
	v_mov_b32_e32 v91, v86
	v_pk_mul_f32 v[98:99], v[78:79], v[86:87]
	v_pk_mul_f32 v[90:91], v[80:81], v[90:91]
	v_pk_mul_f32 v[82:83], v[98:99], v[200:201]
	v_pk_mul_f32 v[84:85], v[90:91], v[202:203]

.LBB0_655:
	v_lshl_add_u64 v[82:83], s[16:17], 2, v[144:145]
	v_mov_b32_e32 v102, v86
	v_mov_b32_e32 v103, v86
	v_pk_mul_f32 v[106:107], v[70:71], v[86:87]
	v_pk_mul_f32 v[102:103], v[72:73], v[102:103]
	v_pk_mul_f32 v[82:83], v[106:107], v[208:209]
	v_pk_mul_f32 v[84:85], v[102:103], v[210:211]
	s_and_b64 vcc, exec, s[12:13]
	s_mov_b64 s[64:65], -1
	s_cbranch_vccz .LBB0_676

.LBB0_672:
	v_lshl_add_u64 v[82:83], s[16:17], 2, v[144:145]
	v_mov_b32_e32 v102, v86
	v_mov_b32_e32 v103, v86
	v_pk_mul_f32 v[106:107], v[74:75], v[86:87]
	v_pk_mul_f32 v[102:103], v[76:77], v[102:103]
	v_pk_mul_f32 v[82:83], v[106:107], v[204:205]
	v_pk_mul_f32 v[84:85], v[102:103], v[206:207]
	s_and_b64 vcc, exec, s[12:13]
	s_mov_b64 s[64:65], -1
	s_cbranch_vccz .LBB0_642

.LBB0_689:
	v_lshl_add_u64 v[82:83], s[16:17], 2, v[144:145]
	v_mov_b32_e32 v102, v86
	v_mov_b32_e32 v103, v86
	v_pk_mul_f32 v[106:107], v[66:67], v[86:87]
	v_pk_mul_f32 v[102:103], v[68:69], v[102:103]
	v_pk_mul_f32 v[82:83], v[106:107], v[212:213]
	v_pk_mul_f32 v[84:85], v[102:103], v[214:215]
	s_and_b64 vcc, exec, s[12:13]
	s_mov_b64 s[10:11], -1
	s_cbranch_vccz .LBB0_659

.LBB0_693:
	s_andn2_b64 vcc, exec, s[8:9]
	s_cbranch_vccnz .LBB0_695
	v_ashrrev_i32_e32 v89, 31, v88
	v_mul_f32_e32 v84, 0x3e38aa3b, v86
	v_lshlrev_b64 v[82:83], 11, v[88:89]
	v_pk_mul_f32 v[86:87], v[80:81], v[84:85] op_sel_hi:[1,0]
	v_pk_mul_f32 v[88:89], v[78:79], v[84:85] op_sel_hi:[1,0]
	v_lshl_add_u64 v[82:83], s[18:19], 0, v[82:83]
	v_lshl_add_u64 v[82:83], s[62:63], 1, v[82:83]
	v_mov_b32_e32 v131, v139
	v_lshl_add_u64 v[82:83], v[82:83], 0, v[130:131]
	v_pk_mul_f32 v[80:81], v[86:87], v[202:203]
	v_pk_mul_f32 v[78:79], v[88:89], v[200:201]
	s_nop 0
	v_cvt_pk_bf16_f32 v78, v78, v79
	v_cvt_pk_bf16_f32 v79, v80, v81
	global_store_dwordx2 v[82:83], v[78:79], off
	v_pk_mul_f32 v[78:79], v[76:77], v[84:85] op_sel_hi:[1,0]
	v_pk_mul_f32 v[80:81], v[74:75], v[84:85] op_sel_hi:[1,0]
	v_pk_mul_f32 v[76:77], v[78:79], v[206:207]
	v_pk_mul_f32 v[74:75], v[80:81], v[204:205]
	s_nop 0
	v_cvt_pk_bf16_f32 v74, v74, v75
	v_cvt_pk_bf16_f32 v75, v76, v77
	global_store_dwordx2 v[82:83], v[74:75], off offset:32
	v_pk_mul_f32 v[74:75], v[72:73], v[84:85] op_sel_hi:[1,0]
	v_pk_mul_f32 v[76:77], v[70:71], v[84:85] op_sel_hi:[1,0]
	v_pk_mul_f32 v[72:73], v[74:75], v[210:211]
	v_pk_mul_f32 v[70:71], v[76:77], v[208:209]
	s_nop 0
	v_cvt_pk_bf16_f32 v70, v70, v71
	v_cvt_pk_bf16_f32 v71, v72, v73
	global_store_dwordx2 v[82:83], v[70:71], off offset:64
	v_pk_mul_f32 v[70:71], v[68:69], v[84:85] op_sel_hi:[1,0]
	v_pk_mul_f32 v[72:73], v[66:67], v[84:85] op_sel_hi:[1,0]
	v_pk_mul_f32 v[68:69], v[70:71], v[214:215]
	v_pk_mul_f32 v[66:67], v[72:73], v[212:213]
	s_nop 0
	v_cvt_pk_bf16_f32 v66, v66, v67
	v_cvt_pk_bf16_f32 v67, v68, v69
	global_store_dwordx2 v[82:83], v[66:67], off offset:96

.LBB0_711:
	s_andn2_b64 vcc, exec, s[8:9]
	s_cbranch_vccnz .LBB0_780
	v_cndmask_b32_e64 v66, 0, 1, s[58:59]
	v_cmp_ne_u32_e64 s[10:11], 1, v66
	v_mov_b64_e32 v[68:69], v[64:65]
	v_mov_b32_e32 v73, v72
	s_andn2_b64 vcc, exec, s[58:59]
	v_mov_b64_e32 v[66:67], v[62:63]
	s_cbranch_vccnz .LBB0_714
	v_lshl_add_u64 v[66:67], s[16:17], 2, v[144:145]
	v_mov_b32_e32 v74, v72
	v_mov_b32_e32 v75, v72
	v_pk_mul_f32 v[80:81], v[62:63], v[72:73]
	v_pk_mul_f32 v[74:75], v[64:65], v[74:75]
	v_pk_mul_f32 v[66:67], v[80:81], v[200:201]
	v_pk_mul_f32 v[68:69], v[74:75], v[202:203]

.LBB0_743:
	v_lshl_add_u64 v[66:67], s[16:17], 2, v[144:145]
	v_mov_b32_e32 v86, v72
	v_mov_b32_e32 v87, v72
	v_pk_mul_f32 v[90:91], v[54:55], v[72:73]
	v_pk_mul_f32 v[86:87], v[56:57], v[86:87]
	v_pk_mul_f32 v[66:67], v[90:91], v[208:209]
	v_pk_mul_f32 v[68:69], v[86:87], v[210:211]
	s_and_b64 vcc, exec, s[12:13]
	s_mov_b64 s[64:65], -1
	s_cbranch_vccz .LBB0_764

.LBB0_760:
	v_lshl_add_u64 v[66:67], s[16:17], 2, v[144:145]
	v_mov_b32_e32 v86, v72
	v_mov_b32_e32 v87, v72
	v_pk_mul_f32 v[90:91], v[58:59], v[72:73]
	v_pk_mul_f32 v[86:87], v[60:61], v[86:87]
	v_pk_mul_f32 v[66:67], v[90:91], v[204:205]
	v_pk_mul_f32 v[68:69], v[86:87], v[206:207]
	s_and_b64 vcc, exec, s[12:13]
	s_mov_b64 s[64:65], -1
	s_cbranch_vccz .LBB0_730

.LBB0_777:
	v_lshl_add_u64 v[66:67], s[16:17], 2, v[144:145]
	v_mov_b32_e32 v86, v72
	v_mov_b32_e32 v87, v72
	v_pk_mul_f32 v[90:91], v[50:51], v[72:73]
	v_pk_mul_f32 v[86:87], v[52:53], v[86:87]
	v_pk_mul_f32 v[66:67], v[90:91], v[212:213]
	v_pk_mul_f32 v[68:69], v[86:87], v[214:215]
	s_and_b64 vcc, exec, s[12:13]
	s_mov_b64 s[10:11], -1
	s_cbranch_vccz .LBB0_747

.LBB0_781:
	s_andn2_b64 vcc, exec, s[8:9]
	s_cbranch_vccnz .LBB0_783
	v_ashrrev_i32_e32 v71, 31, v70
	v_mul_f32_e32 v68, 0x3e38aa3b, v72
	v_lshlrev_b64 v[66:67], 11, v[70:71]
	v_pk_mul_f32 v[70:71], v[64:65], v[68:69] op_sel_hi:[1,0]
	v_pk_mul_f32 v[72:73], v[62:63], v[68:69] op_sel_hi:[1,0]
	v_lshl_add_u64 v[66:67], s[18:19], 0, v[66:67]
	v_lshl_add_u64 v[66:67], s[62:63], 1, v[66:67]
	v_mov_b32_e32 v131, v139
	v_lshl_add_u64 v[66:67], v[66:67], 0, v[130:131]
	v_pk_mul_f32 v[64:65], v[70:71], v[202:203]
	v_pk_mul_f32 v[62:63], v[72:73], v[200:201]
	s_nop 0
	v_cvt_pk_bf16_f32 v62, v62, v63
	v_cvt_pk_bf16_f32 v63, v64, v65
	global_store_dwordx2 v[66:67], v[62:63], off
	v_pk_mul_f32 v[62:63], v[60:61], v[68:69] op_sel_hi:[1,0]
	v_pk_mul_f32 v[64:65], v[58:59], v[68:69] op_sel_hi:[1,0]
	v_pk_mul_f32 v[60:61], v[62:63], v[206:207]
	v_pk_mul_f32 v[58:59], v[64:65], v[204:205]
	s_nop 0
	v_cvt_pk_bf16_f32 v58, v58, v59
	v_cvt_pk_bf16_f32 v59, v60, v61
	global_store_dwordx2 v[66:67], v[58:59], off offset:32
	v_pk_mul_f32 v[58:59], v[56:57], v[68:69] op_sel_hi:[1,0]
	v_pk_mul_f32 v[60:61], v[54:55], v[68:69] op_sel_hi:[1,0]
	v_pk_mul_f32 v[56:57], v[58:59], v[210:211]
	v_pk_mul_f32 v[54:55], v[60:61], v[208:209]
	s_nop 0
	v_cvt_pk_bf16_f32 v54, v54, v55
	v_cvt_pk_bf16_f32 v55, v56, v57
	global_store_dwordx2 v[66:67], v[54:55], off offset:64
	v_pk_mul_f32 v[54:55], v[52:53], v[68:69] op_sel_hi:[1,0]
	v_pk_mul_f32 v[56:57], v[50:51], v[68:69] op_sel_hi:[1,0]
	v_pk_mul_f32 v[52:53], v[54:55], v[214:215]
	v_pk_mul_f32 v[50:51], v[56:57], v[212:213]
	s_nop 0
	v_cvt_pk_bf16_f32 v50, v50, v51
	v_cvt_pk_bf16_f32 v51, v52, v53
	global_store_dwordx2 v[66:67], v[50:51], off offset:96

.LBB0_799:
	s_andn2_b64 vcc, exec, s[8:9]
	s_cbranch_vccnz .LBB0_868
	v_cndmask_b32_e64 v50, 0, 1, s[58:59]
	v_cmp_ne_u32_e64 s[10:11], 1, v50
	v_mov_b64_e32 v[52:53], v[48:49]
	v_mov_b32_e32 v55, v54
	s_andn2_b64 vcc, exec, s[58:59]
	v_mov_b64_e32 v[50:51], v[46:47]
	s_cbranch_vccnz .LBB0_802
	v_lshl_add_u64 v[50:51], s[16:17], 2, v[144:145]
	v_mov_b32_e32 v58, v54
	v_mov_b32_e32 v59, v54
	v_pk_mul_f32 v[64:65], v[46:47], v[54:55]
	v_pk_mul_f32 v[58:59], v[48:49], v[58:59]
	v_pk_mul_f32 v[50:51], v[64:65], v[200:201]
	v_pk_mul_f32 v[52:53], v[58:59], v[202:203]

.LBB0_831:
	v_lshl_add_u64 v[50:51], s[16:17], 2, v[144:145]
	v_mov_b32_e32 v70, v54
	v_mov_b32_e32 v71, v54
	v_pk_mul_f32 v[74:75], v[38:39], v[54:55]
	v_pk_mul_f32 v[70:71], v[40:41], v[70:71]
	v_pk_mul_f32 v[50:51], v[74:75], v[208:209]
	v_pk_mul_f32 v[52:53], v[70:71], v[210:211]
	s_and_b64 vcc, exec, s[12:13]
	s_mov_b64 s[64:65], -1
	s_cbranch_vccz .LBB0_852

.LBB0_848:
	v_lshl_add_u64 v[50:51], s[16:17], 2, v[144:145]
	v_mov_b32_e32 v70, v54
	v_mov_b32_e32 v71, v54
	v_pk_mul_f32 v[74:75], v[42:43], v[54:55]
	v_pk_mul_f32 v[70:71], v[44:45], v[70:71]
	v_pk_mul_f32 v[50:51], v[74:75], v[204:205]
	v_pk_mul_f32 v[52:53], v[70:71], v[206:207]
	s_and_b64 vcc, exec, s[12:13]
	s_mov_b64 s[64:65], -1
	s_cbranch_vccz .LBB0_818

.LBB0_865:
	v_lshl_add_u64 v[50:51], s[16:17], 2, v[144:145]
	v_mov_b32_e32 v70, v54
	v_mov_b32_e32 v71, v54
	v_pk_mul_f32 v[74:75], v[34:35], v[54:55]
	v_pk_mul_f32 v[70:71], v[36:37], v[70:71]
	v_pk_mul_f32 v[50:51], v[74:75], v[212:213]
	v_pk_mul_f32 v[52:53], v[70:71], v[214:215]
	s_and_b64 vcc, exec, s[12:13]
	s_mov_b64 s[10:11], -1
	s_cbranch_vccz .LBB0_835

.LBB0_869:
	s_andn2_b64 vcc, exec, s[8:9]
	s_cbranch_vccnz .LBB0_871
	v_ashrrev_i32_e32 v57, 31, v56
	v_mul_f32_e32 v52, 0x3e38aa3b, v54
	v_lshlrev_b64 v[50:51], 11, v[56:57]
	v_pk_mul_f32 v[54:55], v[48:49], v[52:53] op_sel_hi:[1,0]
	v_pk_mul_f32 v[56:57], v[46:47], v[52:53] op_sel_hi:[1,0]
	v_lshl_add_u64 v[50:51], s[18:19], 0, v[50:51]
	v_lshl_add_u64 v[50:51], s[62:63], 1, v[50:51]
	v_mov_b32_e32 v131, v139
	v_lshl_add_u64 v[50:51], v[50:51], 0, v[130:131]
	v_pk_mul_f32 v[48:49], v[54:55], v[202:203]
	v_pk_mul_f32 v[46:47], v[56:57], v[200:201]
	s_nop 0
	v_cvt_pk_bf16_f32 v46, v46, v47
	v_cvt_pk_bf16_f32 v47, v48, v49
	global_store_dwordx2 v[50:51], v[46:47], off
	v_pk_mul_f32 v[46:47], v[44:45], v[52:53] op_sel_hi:[1,0]
	v_pk_mul_f32 v[48:49], v[42:43], v[52:53] op_sel_hi:[1,0]
	v_pk_mul_f32 v[44:45], v[46:47], v[206:207]
	v_pk_mul_f32 v[42:43], v[48:49], v[204:205]
	s_nop 0
	v_cvt_pk_bf16_f32 v42, v42, v43
	v_cvt_pk_bf16_f32 v43, v44, v45
	global_store_dwordx2 v[50:51], v[42:43], off offset:32
	v_pk_mul_f32 v[42:43], v[40:41], v[52:53] op_sel_hi:[1,0]
	v_pk_mul_f32 v[44:45], v[38:39], v[52:53] op_sel_hi:[1,0]
	v_pk_mul_f32 v[40:41], v[42:43], v[210:211]
	v_pk_mul_f32 v[38:39], v[44:45], v[208:209]
	s_nop 0
	v_cvt_pk_bf16_f32 v38, v38, v39
	v_cvt_pk_bf16_f32 v39, v40, v41
	global_store_dwordx2 v[50:51], v[38:39], off offset:64
	v_pk_mul_f32 v[38:39], v[36:37], v[52:53] op_sel_hi:[1,0]
	v_pk_mul_f32 v[40:41], v[34:35], v[52:53] op_sel_hi:[1,0]
	v_pk_mul_f32 v[36:37], v[38:39], v[214:215]
	v_pk_mul_f32 v[34:35], v[40:41], v[212:213]
	s_nop 0
	v_cvt_pk_bf16_f32 v34, v34, v35
	v_cvt_pk_bf16_f32 v35, v36, v37
	global_store_dwordx2 v[50:51], v[34:35], off offset:96

.LBB0_887:
	s_andn2_b64 vcc, exec, s[8:9]
	s_cbranch_vccnz .LBB0_956
	v_cndmask_b32_e64 v34, 0, 1, s[58:59]
	v_cmp_ne_u32_e64 s[10:11], 1, v34
	v_mov_b64_e32 v[36:37], v[32:33]
	v_mov_b32_e32 v39, v38
	s_andn2_b64 vcc, exec, s[58:59]
	v_mov_b64_e32 v[34:35], v[30:31]
	s_cbranch_vccnz .LBB0_890
	v_lshl_add_u64 v[34:35], s[16:17], 2, v[144:145]
	v_mov_b32_e32 v42, v38
	v_mov_b32_e32 v43, v38
	v_pk_mul_f32 v[48:49], v[30:31], v[38:39]
	v_pk_mul_f32 v[42:43], v[32:33], v[42:43]
	v_pk_mul_f32 v[34:35], v[48:49], v[200:201]
	v_pk_mul_f32 v[36:37], v[42:43], v[202:203]

.LBB0_919:
	v_lshl_add_u64 v[34:35], s[16:17], 2, v[144:145]
	v_mov_b32_e32 v54, v38
	v_mov_b32_e32 v55, v38
	v_pk_mul_f32 v[58:59], v[22:23], v[38:39]
	v_pk_mul_f32 v[54:55], v[24:25], v[54:55]
	v_pk_mul_f32 v[34:35], v[58:59], v[208:209]
	v_pk_mul_f32 v[36:37], v[54:55], v[210:211]
	s_and_b64 vcc, exec, s[12:13]
	s_mov_b64 s[64:65], -1
	s_cbranch_vccz .LBB0_940

.LBB0_936:
	v_lshl_add_u64 v[34:35], s[16:17], 2, v[144:145]
	v_mov_b32_e32 v54, v38
	v_mov_b32_e32 v55, v38
	v_pk_mul_f32 v[58:59], v[26:27], v[38:39]
	v_pk_mul_f32 v[54:55], v[28:29], v[54:55]
	v_pk_mul_f32 v[34:35], v[58:59], v[204:205]
	v_pk_mul_f32 v[36:37], v[54:55], v[206:207]
	s_and_b64 vcc, exec, s[12:13]
	s_mov_b64 s[64:65], -1
	s_cbranch_vccz .LBB0_906

.LBB0_953:
	v_lshl_add_u64 v[34:35], s[16:17], 2, v[144:145]
	v_mov_b32_e32 v54, v38
	v_mov_b32_e32 v55, v38
	v_pk_mul_f32 v[58:59], v[18:19], v[38:39]
	v_pk_mul_f32 v[54:55], v[20:21], v[54:55]
	v_pk_mul_f32 v[34:35], v[58:59], v[212:213]
	v_pk_mul_f32 v[36:37], v[54:55], v[214:215]
	s_and_b64 vcc, exec, s[12:13]
	s_mov_b64 s[10:11], -1
	s_cbranch_vccz .LBB0_923

.LBB0_957:
	s_andn2_b64 vcc, exec, s[8:9]
	s_cbranch_vccnz .LBB0_959
	v_ashrrev_i32_e32 v41, 31, v40
	v_mul_f32_e32 v36, 0x3e38aa3b, v38
	v_lshlrev_b64 v[34:35], 11, v[40:41]
	v_pk_mul_f32 v[38:39], v[32:33], v[36:37] op_sel_hi:[1,0]
	v_pk_mul_f32 v[40:41], v[30:31], v[36:37] op_sel_hi:[1,0]
	v_lshl_add_u64 v[34:35], s[18:19], 0, v[34:35]
	v_lshl_add_u64 v[34:35], s[62:63], 1, v[34:35]
	v_mov_b32_e32 v131, v139
	v_lshl_add_u64 v[34:35], v[34:35], 0, v[130:131]
	v_pk_mul_f32 v[32:33], v[38:39], v[202:203]
	v_pk_mul_f32 v[30:31], v[40:41], v[200:201]
	s_nop 0
	v_cvt_pk_bf16_f32 v30, v30, v31
	v_cvt_pk_bf16_f32 v31, v32, v33
	global_store_dwordx2 v[34:35], v[30:31], off
	v_pk_mul_f32 v[30:31], v[28:29], v[36:37] op_sel_hi:[1,0]
	v_pk_mul_f32 v[32:33], v[26:27], v[36:37] op_sel_hi:[1,0]
	v_pk_mul_f32 v[28:29], v[30:31], v[206:207]
	v_pk_mul_f32 v[26:27], v[32:33], v[204:205]
	s_nop 0
	v_cvt_pk_bf16_f32 v26, v26, v27
	v_cvt_pk_bf16_f32 v27, v28, v29
	global_store_dwordx2 v[34:35], v[26:27], off offset:32
	v_pk_mul_f32 v[26:27], v[24:25], v[36:37] op_sel_hi:[1,0]
	v_pk_mul_f32 v[28:29], v[22:23], v[36:37] op_sel_hi:[1,0]
	v_pk_mul_f32 v[24:25], v[26:27], v[210:211]
	v_pk_mul_f32 v[22:23], v[28:29], v[208:209]
	s_nop 0
	v_cvt_pk_bf16_f32 v22, v22, v23
	v_cvt_pk_bf16_f32 v23, v24, v25
	global_store_dwordx2 v[34:35], v[22:23], off offset:64
	v_pk_mul_f32 v[22:23], v[20:21], v[36:37] op_sel_hi:[1,0]
	v_pk_mul_f32 v[24:25], v[18:19], v[36:37] op_sel_hi:[1,0]
	v_pk_mul_f32 v[20:21], v[22:23], v[214:215]
	v_pk_mul_f32 v[18:19], v[24:25], v[212:213]
	s_nop 0
	v_cvt_pk_bf16_f32 v18, v18, v19
	v_cvt_pk_bf16_f32 v19, v20, v21
	global_store_dwordx2 v[34:35], v[18:19], off offset:96

.LBB0_975:
	s_andn2_b64 vcc, exec, s[0:1]
	s_cbranch_vccnz .LBB0_1044
	v_cndmask_b32_e64 v18, 0, 1, s[58:59]
	v_cmp_ne_u32_e64 s[2:3], 1, v18
	v_mov_b64_e32 v[20:21], v[16:17]
	v_mov_b32_e32 v25, v24
	s_andn2_b64 vcc, exec, s[58:59]
	v_lshl_add_u64 v[36:37], s[16:17], 2, v[144:145]
	v_mov_b64_e32 v[18:19], v[14:15]
	s_cbranch_vccnz .LBB0_978
	v_mov_b32_e32 v26, v24
	v_mov_b32_e32 v27, v24
	v_pk_mul_f32 v[34:35], v[14:15], v[24:25]
	v_pk_mul_f32 v[26:27], v[16:17], v[26:27]
	v_pk_mul_f32 v[18:19], v[34:35], v[200:201]
	v_pk_mul_f32 v[20:21], v[26:27], v[202:203]

.LBB0_1007:
	v_mov_b32_e32 v44, v24
	v_mov_b32_e32 v45, v24
	v_pk_mul_f32 v[46:47], v[6:7], v[24:25]
	v_pk_mul_f32 v[44:45], v[8:9], v[44:45]
	v_pk_mul_f32 v[18:19], v[46:47], v[208:209]
	v_pk_mul_f32 v[20:21], v[44:45], v[210:211]
	s_and_b64 vcc, exec, s[10:11]
	s_mov_b64 s[12:13], -1
	s_cbranch_vccz .LBB0_1028

.LBB0_1024:
	v_mov_b32_e32 v40, v24
	v_mov_b32_e32 v41, v24
	v_pk_mul_f32 v[44:45], v[10:11], v[24:25]
	v_pk_mul_f32 v[40:41], v[12:13], v[40:41]
	v_pk_mul_f32 v[18:19], v[44:45], v[204:205]
	v_pk_mul_f32 v[20:21], v[40:41], v[206:207]
	s_and_b64 vcc, exec, s[10:11]
	s_mov_b64 s[12:13], -1
	s_cbranch_vccz .LBB0_994

.LBB0_1041:
	v_mov_b32_e32 v36, v24
	v_mov_b32_e32 v37, v24
	v_pk_mul_f32 v[44:45], v[2:3], v[24:25]
	v_pk_mul_f32 v[36:37], v[4:5], v[36:37]
	v_pk_mul_f32 v[18:19], v[44:45], v[212:213]
	v_pk_mul_f32 v[20:21], v[36:37], v[214:215]
	s_and_b64 vcc, exec, s[10:11]
	s_mov_b64 s[2:3], -1
	s_cbranch_vccz .LBB0_1011

.LBB0_1045:
	s_andn2_b64 vcc, exec, s[2:3]
	s_cbranch_vccnz .LBB0_334
	v_ashrrev_i32_e32 v23, 31, v22
	v_mul_f32_e32 v24, 0x3e38aa3b, v24
	v_lshlrev_b64 v[22:23], 11, v[22:23]
	v_pk_mul_f32 v[16:17], v[16:17], v[24:25] op_sel_hi:[1,0]
	v_pk_mul_f32 v[14:15], v[14:15], v[24:25] op_sel_hi:[1,0]
	v_lshl_add_u64 v[22:23], s[18:19], 0, v[22:23]
	v_mov_b32_e32 v131, v139
	v_lshl_add_u64 v[22:23], s[62:63], 1, v[22:23]
	v_lshl_add_u64 v[22:23], v[22:23], 0, v[130:131]
	v_pk_mul_f32 v[12:13], v[12:13], v[24:25] op_sel_hi:[1,0]
	v_pk_mul_f32 v[10:11], v[10:11], v[24:25] op_sel_hi:[1,0]
	v_pk_mul_f32 v[8:9], v[8:9], v[24:25] op_sel_hi:[1,0]
	v_pk_mul_f32 v[6:7], v[6:7], v[24:25] op_sel_hi:[1,0]
	v_pk_mul_f32 v[4:5], v[4:5], v[24:25] op_sel_hi:[1,0]
	v_pk_mul_f32 v[2:3], v[2:3], v[24:25] op_sel_hi:[1,0]
	v_pk_mul_f32 v[16:17], v[16:17], v[202:203]
	v_pk_mul_f32 v[14:15], v[14:15], v[200:201]
	s_nop 0
	v_cvt_pk_bf16_f32 v14, v14, v15
	v_cvt_pk_bf16_f32 v15, v16, v17
	global_store_dwordx2 v[22:23], v[14:15], off
	v_pk_mul_f32 v[12:13], v[12:13], v[206:207]
	v_pk_mul_f32 v[10:11], v[10:11], v[204:205]
	s_nop 0
	v_cvt_pk_bf16_f32 v10, v10, v11
	v_cvt_pk_bf16_f32 v11, v12, v13
	global_store_dwordx2 v[22:23], v[10:11], off offset:32
	v_pk_mul_f32 v[8:9], v[8:9], v[210:211]
	v_pk_mul_f32 v[6:7], v[6:7], v[208:209]
	s_nop 0
	v_cvt_pk_bf16_f32 v6, v6, v7
	v_cvt_pk_bf16_f32 v7, v8, v9
	global_store_dwordx2 v[22:23], v[6:7], off offset:64
	v_pk_mul_f32 v[4:5], v[4:5], v[214:215]
	v_pk_mul_f32 v[2:3], v[2:3], v[212:213]
	s_nop 0
	v_cvt_pk_bf16_f32 v2, v2, v3
	v_cvt_pk_bf16_f32 v3, v4, v5
	global_store_dwordx2 v[22:23], v[2:3], off offset:96
	s_branch .LBB0_334
